# K loops without s_setprio flips + one static s_setprio 1 for waves 4..7 at kernel entry
# baseline (speedup 1.0000x reference)
_Z14fwd_megakernel6Params:
	s_mov_b32 s92, s2
	v_readfirstlane_b32 s101, v0
	s_nop 3
	s_and_b32 s101, s101, 0x3ff
	s_lshr_b32 s101, s101, 6
	s_cmp_ge_u32 s101, 4
	s_cbranch_scc0 .Lprio_done
	s_setprio 1
.Lprio_done:
	s_mov_b32 s100, 0
	s_mov_b32 s99, 0
	s_load_dwordx8 s[84:91], s[0:1], 0x80
	s_load_dword s2, s[0:1], 0xa0
	s_load_dwordx16 s[56:71], s[0:1], 0x0
	s_load_dwordx16 s[20:35], s[0:1], 0x40
	v_and_b32_e32 v162, 0x3ff, v0
	v_cmp_eq_u32_e64 s[4:5], 0, v162
	s_waitcnt lgkmcnt(0)
	v_writelane_b32 v251, s2, 0
	s_add_u32 s2, s0, 0x98
	s_addc_u32 s3, s1, 0
	v_writelane_b32 v251, s2, 1
	s_nop 1
	v_writelane_b32 v251, s3, 2
	s_mov_b64 s[2:3], exec
	v_writelane_b32 v251, s4, 3
	s_nop 1
	v_writelane_b32 v251, s5, 4
	s_and_b64 s[4:5], s[2:3], s[4:5]
	s_mov_b64 exec, s[4:5]
	s_cbranch_execz .LBB0_2
	v_mov_b32_e32 v2, 0
	v_mov_b32_e32 v3, v2
	v_mov_b32_e32 v4, v2
	v_mov_b32_e32 v5, v2
	v_mov_b32_e32 v1, 0x20000
	ds_write_b128 v1, v[2:5]
